# scan pass 1 stage S2: operand-image reads issued together behind counted waits (state waves and triangular-matrix waves)
# baseline (speedup 1.0000x reference)
; #define LAS __attribute__((address_space(3)))
; __device__ __forceinline__ void scan_pass1(const ScanP& sp, int b, int h, int seg, LAS unsigned char* lds) {
;     ...
;             f32x4 ein, eex, einv;
; #pragma unroll
;             for (int e = 0; e < 4; ++e) { ein[e] = ex2(cl[e]); eex[e] = ex2(cl[e] - lw[e]); einv[e] = __builtin_amdgcn_rcpf(ein[e]); }
;             const f32x4 kkt = kkn * eex, rt = r4 * ein, kh = kp * einv, bh = bb * einv;
;             u32x2 o;
;             o.x = pk2(kkt[0], kkt[1]); o.y = pk2(kkt[2], kkt[3]); *(LAS u32x2*)(lds + O_KK + (tt * 72 + j4) * 2) = o;
;             o.x = pk2(rt[0], rt[1]); o.y = pk2(rt[2], rt[3]); *(LAS u32x2*)(lds + O_R + (tt * 72 + j4) * 2) = o;
;             o.x = pk2(kh[0], kh[1]); o.y = pk2(kh[2], kh[3]); *(LAS u32x2*)(lds + O_K + (tt * 72 + j4) * 2) = o;
;             const unsigned k01 = o.x, k23 = o.y;
;             o.x = pk2(bh[0], bh[1]); o.y = pk2(bh[2], bh[3]); *(LAS u32x2*)(lds + O_B + (tt * 72 + j4) * 2) = o;
;             const unsigned nb01 = pk2(-bh[0], -bh[1]), nb23 = pk2(-bh[2], -bh[3]);
;             const unsigned v01 = pk2(v4[0], v4[1]), v23 = pk2(v4[2], v4[3]);
;             LAS unsigned short* kt = (LAS unsigned short*)(lds + O_KT) + j4 * 40 + tt;
;             kt[0] = (unsigned short)(k01 & 0xffffu); kt[40] = (unsigned short)(k01 >> 16); kt[80] = (unsigned short)(k23 & 0xffffu); kt[120] = (unsigned short)(k23 >> 16);
;             LAS unsigned short* bt = (LAS unsigned short*)(lds + O_BT) + j4 * 40 + tt;
;             bt[0] = (unsigned short)(nb01 & 0xffffu); bt[40] = (unsigned short)(nb01 >> 16); bt[80] = (unsigned short)(nb23 & 0xffffu); bt[120] = (unsigned short)(nb23 >> 16);
;             LAS unsigned short* vt = (LAS unsigned short*)(lds + O_VT) + j4 * 40 + tt;
;             vt[0] = (unsigned short)(v01 & 0xffffu); vt[40] = (unsigned short)(v01 >> 16); vt[80] = (unsigned short)(v23 & 0xffffu); vt[120] = (unsigned short)(v23 >> 16);
;             if (tt == 31) *(LAS f32x4*)(gam + j4) = ein;
;     ...
;         } else {
;             const int job = w - 4;
;             const int oa = (job == 0 || job == 2) ? O_K : O_B, ob = (job < 2) ? O_KK : O_R;
;             f32x16 Z;
; #pragma unroll
;             for (int i = 0; i < 16; ++i) Z[i] = 0.f;
; #pragma unroll
;             for (int ks = 0; ks < 4; ++ks) {
;                 const int off = (ln * 72 + ks * 16 + hh * 8) * 2;
.LBB0_266:
	s_or_b64 exec, exec, s[0:1]
	v_sub_f32_e32 v0, v80, v100
	v_exp_f32_e32 v104, v80
	v_exp_f32_e32 v105, v81
	v_exp_f32_e32 v2, v0
	v_sub_f32_e32 v0, v81, v101
	v_exp_f32_e32 v106, v82
	v_exp_f32_e32 v107, v83
	v_exp_f32_e32 v3, v0
	v_sub_f32_e32 v0, v82, v102
	v_exp_f32_e32 v82, v0
	v_sub_f32_e32 v0, v83, v103
	v_exp_f32_e32 v83, v0
	v_rcp_f32_e32 v80, v104
	v_rcp_f32_e32 v81, v105
	v_rcp_f32_e32 v110, v106
	v_rcp_f32_e32 v111, v107
	v_pk_mul_f32 v[82:83], v[132:133], v[82:83]
	v_pk_mul_f32 v[2:3], v[130:131], v[2:3]
	s_waitcnt lgkmcnt(0)
	v_pk_mul_f32 v[78:79], v[78:79], v[106:107]
	v_pk_mul_f32 v[76:77], v[76:77], v[104:105]
	v_pk_mul_f32 v[74:75], v[74:75], v[110:111]
	v_pk_mul_f32 v[72:73], v[72:73], v[80:81]
	v_pk_mul_f32 v[110:111], v[136:137], v[110:111]
	v_pk_mul_f32 v[80:81], v[134:135], v[80:81]
	v_cvt_pk_bf16_f32 v2, v2, v3
	v_cvt_pk_bf16_f32 v3, v82, v83
	v_add_u32_e32 v0, 0, v163
	v_cvt_pk_bf16_f32 v76, v76, v77
	v_cvt_pk_bf16_f32 v77, v78, v79
	ds_write2st64_b64 v0, v[2:3], v[76:77] offset0:64 offset1:73
	v_cvt_pk_bf16_f32 v2, v72, v73
	v_cvt_pk_bf16_f32 v3, v74, v75
	v_cvt_pk_bf16_f32 v72, v80, v81
	v_cvt_pk_bf16_f32 v73, v110, v111
	ds_write2st64_b64 v0, v[2:3], v[72:73] offset0:82 offset1:91
	v_xor_b32_e32 v0, 0x80000000, v81
	v_xor_b32_e32 v72, 0x80000000, v80
	v_cvt_pk_bf16_f32 v0, v72, v0
	v_xor_b32_e32 v72, 0x80000000, v110
	v_xor_b32_e32 v73, 0x80000000, v111
	v_cvt_pk_bf16_f32 v72, v72, v73
	v_cvt_pk_bf16_f32 v68, v68, v69
	v_cvt_pk_bf16_f32 v69, v70, v71
	ds_write_b16 v164, v2 offset:51200
	ds_write_b16_d16_hi v164, v2 offset:51280
	ds_write_b16 v164, v3 offset:51360
	ds_write_b16_d16_hi v164, v3 offset:51440
	ds_write_b16 v164, v0 offset:56320
	ds_write_b16_d16_hi v164, v0 offset:56400
	ds_write_b16 v164, v72 offset:56480
	ds_write_b16_d16_hi v164, v72 offset:56560
	ds_write_b16 v164, v68 offset:61440
	ds_write_b16_d16_hi v164, v68 offset:61520
	ds_write_b16 v164, v69 offset:61600
	ds_write_b16_d16_hi v164, v69 offset:61680
	s_and_saveexec_b64 s[0:1], s[52:53]
	ds_write_b128 v165, v[104:107]
	s_or_b64 exec, exec, s[0:1]
	v_mul_u32_u24_e32 v0, 0x90, v189
	s_andn2_b64 vcc, exec, s[56:57]
	s_mov_b64 s[0:1], -1
	s_waitcnt lgkmcnt(0)
	s_barrier
	s_cbranch_vccnz .LBB0_284
	v_lshl_add_u32 v2, v188, 4, v0
	v_add_u32_e32 v3, s65, v2
	v_add_u32_e32 v2, s77, v2
	ds_read_b128 v[68:71], v3
	ds_read_b128 v[72:75], v2
	ds_read_b128 v[104:107], v3 offset:32
	ds_read_b128 v[110:113], v2 offset:32
	ds_read_b128 v[230:233], v3 offset:64
	ds_read_b128 v[234:237], v2 offset:64
	ds_read_b128 v[238:241], v3 offset:96
	ds_read_b128 v[242:245], v2 offset:96
	s_mov_b64 s[78:79], -1
	s_and_b64 vcc, exec, s[72:73]
	s_waitcnt lgkmcnt(6)
	v_mfma_f32_32x32x16_bf16 v[68:83], v[68:71], v[72:75], 0
	s_waitcnt lgkmcnt(4)
	v_mfma_f32_32x32x16_bf16 v[68:83], v[104:107], v[110:113], v[68:83]
	s_waitcnt lgkmcnt(2)
	v_mfma_f32_32x32x16_bf16 v[68:83], v[230:233], v[234:237], v[68:83]
	v_lshlrev_b32_e32 v2, 2, v188
	v_or_b32_e32 v117, 2, v2
	v_or_b32_e32 v116, 3, v2
	v_add_u32_e32 v115, 8, v2
	v_add_u32_e32 v109, 10, v2
	v_add_u32_e32 v3, 11, v2
	s_waitcnt lgkmcnt(0)
	v_mfma_f32_32x32x16_bf16 v[68:83], v[238:241], v[242:245], v[68:83]
	v_add_u32_e32 v113, 9, v2
	v_add_u32_e32 v111, 16, v2
	v_add_u32_e32 v106, 17, v2
	v_add_u32_e32 v110, 18, v2
	v_add_u32_e32 v104, 19, v2
	v_add_u32_e32 v114, 24, v2
	v_add_u32_e32 v112, 25, v2
	v_add_u32_e32 v107, 26, v2
	v_add_u32_e32 v105, 27, v2
	v_cmp_lt_i32_e64 s[40:41], v2, v189
	v_cmp_lt_i32_e64 s[50:51], v117, v189
	v_cmp_lt_i32_e64 s[48:49], v116, v189
	v_cmp_lt_i32_e64 s[46:47], v115, v189
	v_cmp_lt_i32_e64 s[44:45], v113, v189
	v_cmp_lt_i32_e64 s[42:43], v109, v189
	v_cmp_lt_i32_e64 s[38:39], v3, v189
	v_cmp_lt_i32_e64 s[36:37], v111, v189
	v_cmp_lt_i32_e64 s[34:35], v106, v189
	v_cmp_lt_i32_e64 s[30:31], v110, v189
	v_cmp_lt_i32_e64 s[28:29], v104, v189
	v_cmp_lt_i32_e64 s[26:27], v114, v189
	v_cmp_lt_i32_e64 s[24:25], v112, v189
	v_cmp_lt_i32_e64 s[22:23], v107, v189
	v_cmp_lt_i32_e64 s[0:1], v105, v189
	s_cbranch_vccz .LBB0_271
; #define LAS __attribute__((address_space(3)))
; __device__ __forceinline__ unsigned pk2(float lo, float hi) { f32x2 v = {lo, hi}; bf16x2_t b = __builtin_convertvector(v, bf16x2_t); return __builtin_bit_cast(unsigned, b); }
; __device__ __forceinline__ void scan_pass1(const ScanP& sp, int b, int h, int seg, LAS unsigned char* lds) {
;     ...
;                 const int oo = (job == 0) ? O_MK : (job == 2) ? O_NK : O_NB;
; #pragma unroll
;                 for (int g = 0; g < 4; ++g) {
;                     float z[4];
; #pragma unroll
;                     for (int e = 0; e < 4; ++e) {
;                         const int s = 8 * g + 4 * hh + e;
;                         const bool keep = (job == 0) ? (s < ln) : (s <= ln);
;                         float v = keep ? Z[4 * g + e] : 0.f; if (job == 3) v = -v; z[e] = v;
;                     }
;                     u32x2 o; o.x = pk2(z[0], z[1]); o.y = pk2(z[2], z[3]);
;                     *(LAS u32x2*)(lds + oo + (ln * 40 + 8 * g + 4 * hh) * 2) = o;
;                 }
	v_lshlrev_b32_e32 v118, 3, v188
	v_mul_u32_u24_e32 v119, 0x50, v189
	v_cmp_le_i32_e32 vcc, v2, v189
	v_add3_u32 v121, s33, v118, v119
	v_cndmask_b32_e64 v118, 0, 1, s[40:41]
	v_cndmask_b32_e64 v119, 0, 1, vcc
	v_cndmask_b32_e64 v118, v119, v118, s[4:5]
	v_and_b32_e32 v118, 1, v118
	v_cmp_eq_u32_e32 vcc, 1, v118
	v_or_b32_e32 v119, v2, v166
	v_cndmask_b32_e64 v123, 0, 1, s[50:51]
	v_cndmask_b32_e32 v118, 0, v68, vcc
	v_cmp_gt_i32_e32 vcc, v189, v119
	v_cndmask_b32_e64 v118, v118, -v118, s[74:75]
	s_mov_b64 s[78:79], 0
	v_cndmask_b32_e32 v119, 0, v69, vcc
	v_cmp_le_i32_e32 vcc, v117, v189
	v_cndmask_b32_e64 v119, v119, -v119, s[74:75]
	v_cvt_pk_bf16_f32 v118, v118, v119
	v_cndmask_b32_e64 v150, 0, 1, vcc
	v_cndmask_b32_e64 v123, v150, v123, s[4:5]
	v_and_b32_e32 v123, 1, v123
	v_cmp_eq_u32_e32 vcc, 1, v123
	v_cndmask_b32_e64 v150, 0, 1, s[48:49]
	s_nop 0
	v_cndmask_b32_e32 v123, 0, v70, vcc
	v_cmp_le_i32_e32 vcc, v116, v189
	v_cndmask_b32_e64 v123, v123, -v123, s[74:75]
	s_nop 0
	v_cndmask_b32_e64 v151, 0, 1, vcc
	v_cndmask_b32_e64 v150, v151, v150, s[4:5]
	v_and_b32_e32 v150, 1, v150
	v_cmp_eq_u32_e32 vcc, 1, v150
	s_nop 1
	v_cndmask_b32_e32 v150, 0, v71, vcc
	v_cndmask_b32_e64 v150, v150, -v150, s[74:75]
	v_cmp_le_i32_e32 vcc, v115, v189
	v_cvt_pk_bf16_f32 v119, v123, v150
	v_cndmask_b32_e64 v123, 0, 1, s[46:47]
	v_cndmask_b32_e64 v150, 0, 1, vcc
	v_cndmask_b32_e64 v123, v150, v123, s[4:5]
	v_and_b32_e32 v123, 1, v123
	v_cmp_eq_u32_e32 vcc, 1, v123
	v_cndmask_b32_e64 v150, 0, 1, s[44:45]
	s_nop 0
	v_cndmask_b32_e32 v123, 0, v72, vcc
	v_cmp_le_i32_e32 vcc, v113, v189
	v_cndmask_b32_e64 v123, v123, -v123, s[74:75]
	s_nop 0
	v_cndmask_b32_e64 v151, 0, 1, vcc
	v_cndmask_b32_e64 v150, v151, v150, s[4:5]
	v_and_b32_e32 v150, 1, v150
	v_cmp_eq_u32_e32 vcc, 1, v150
	v_cndmask_b32_e64 v151, 0, 1, s[42:43]
	s_nop 0
	v_cndmask_b32_e32 v150, 0, v73, vcc
	v_cmp_le_i32_e32 vcc, v109, v189
	v_cndmask_b32_e64 v150, v150, -v150, s[74:75]
	v_cvt_pk_bf16_f32 v150, v123, v150
	v_cndmask_b32_e64 v152, 0, 1, vcc
	v_cndmask_b32_e64 v151, v152, v151, s[4:5]
	v_and_b32_e32 v151, 1, v151
	v_cmp_eq_u32_e32 vcc, 1, v151
	v_cndmask_b32_e64 v152, 0, 1, s[38:39]
	s_nop 0
	v_cndmask_b32_e32 v151, 0, v74, vcc
	v_cmp_le_i32_e32 vcc, v3, v189
	v_cndmask_b32_e64 v151, v151, -v151, s[74:75]
	s_nop 0
	v_cndmask_b32_e64 v153, 0, 1, vcc
	v_cndmask_b32_e64 v152, v153, v152, s[4:5]
	v_and_b32_e32 v152, 1, v152
	v_cmp_eq_u32_e32 vcc, 1, v152
	s_nop 1
	v_cndmask_b32_e32 v152, 0, v75, vcc
	v_cndmask_b32_e64 v152, v152, -v152, s[74:75]
	v_cvt_pk_bf16_f32 v151, v151, v152
	v_cmp_le_i32_e32 vcc, v111, v189
	ds_write2_b64 v121, v[118:119], v[150:151] offset1:2
	v_cndmask_b32_e64 v118, 0, 1, s[36:37]
	v_cndmask_b32_e64 v119, 0, 1, vcc
	v_cndmask_b32_e64 v118, v119, v118, s[4:5]
	v_and_b32_e32 v118, 1, v118
	v_cmp_eq_u32_e32 vcc, 1, v118
	v_cndmask_b32_e64 v119, 0, 1, s[34:35]
	s_nop 0
	v_cndmask_b32_e32 v118, 0, v76, vcc
	v_cmp_le_i32_e32 vcc, v106, v189
	v_cndmask_b32_e64 v118, v118, -v118, s[74:75]
	s_nop 0
	v_cndmask_b32_e64 v123, 0, 1, vcc
	v_cndmask_b32_e64 v119, v123, v119, s[4:5]
	v_and_b32_e32 v119, 1, v119
	v_cmp_eq_u32_e32 vcc, 1, v119
	v_cndmask_b32_e64 v123, 0, 1, s[30:31]
	s_nop 0
	v_cndmask_b32_e32 v119, 0, v77, vcc
	v_cmp_le_i32_e32 vcc, v110, v189
	v_cndmask_b32_e64 v119, v119, -v119, s[74:75]
	v_cvt_pk_bf16_f32 v118, v118, v119
	v_cndmask_b32_e64 v150, 0, 1, vcc
	v_cndmask_b32_e64 v123, v150, v123, s[4:5]
	v_and_b32_e32 v123, 1, v123
	v_cmp_eq_u32_e32 vcc, 1, v123
	v_cndmask_b32_e64 v150, 0, 1, s[28:29]
	s_nop 0
	v_cndmask_b32_e32 v123, 0, v78, vcc
	v_cmp_le_i32_e32 vcc, v104, v189
	v_cndmask_b32_e64 v123, v123, -v123, s[74:75]
	s_nop 0
	v_cndmask_b32_e64 v151, 0, 1, vcc
	v_cndmask_b32_e64 v150, v151, v150, s[4:5]
	v_and_b32_e32 v150, 1, v150
	v_cmp_eq_u32_e32 vcc, 1, v150
	s_nop 1
	v_cndmask_b32_e32 v150, 0, v79, vcc
	v_cndmask_b32_e64 v150, v150, -v150, s[74:75]
	v_cmp_le_i32_e32 vcc, v114, v189
	v_cvt_pk_bf16_f32 v119, v123, v150
	v_cndmask_b32_e64 v123, 0, 1, s[26:27]
	v_cndmask_b32_e64 v150, 0, 1, vcc
	v_cndmask_b32_e64 v123, v150, v123, s[4:5]
	v_and_b32_e32 v123, 1, v123
	v_cmp_eq_u32_e32 vcc, 1, v123
	v_cndmask_b32_e64 v150, 0, 1, s[24:25]
	s_nop 0
	v_cndmask_b32_e32 v123, 0, v80, vcc
	v_cmp_le_i32_e32 vcc, v112, v189
	v_cndmask_b32_e64 v123, v123, -v123, s[74:75]
	s_nop 0
	v_cndmask_b32_e64 v151, 0, 1, vcc
	v_cndmask_b32_e64 v150, v151, v150, s[4:5]
	v_and_b32_e32 v150, 1, v150
	v_cmp_eq_u32_e32 vcc, 1, v150
	v_cndmask_b32_e64 v151, 0, 1, s[22:23]
	s_nop 0
	v_cndmask_b32_e32 v150, 0, v81, vcc
	v_cmp_le_i32_e32 vcc, v107, v189
	v_cndmask_b32_e64 v150, v150, -v150, s[74:75]
	v_cvt_pk_bf16_f32 v150, v123, v150
	v_cndmask_b32_e64 v152, 0, 1, vcc
	v_cndmask_b32_e64 v151, v152, v151, s[4:5]
	v_and_b32_e32 v151, 1, v151
	v_cmp_eq_u32_e32 vcc, 1, v151
	v_cndmask_b32_e64 v152, 0, 1, s[0:1]
	s_nop 0
	v_cndmask_b32_e32 v151, 0, v82, vcc
	v_cmp_le_i32_e32 vcc, v105, v189
	v_cndmask_b32_e64 v151, v151, -v151, s[74:75]
	s_nop 0
	v_cndmask_b32_e64 v153, 0, 1, vcc
	v_cndmask_b32_e64 v152, v153, v152, s[4:5]
	v_and_b32_e32 v152, 1, v152
	v_cmp_eq_u32_e32 vcc, 1, v152
	s_nop 1
	v_cndmask_b32_e32 v152, 0, v83, vcc
	v_cndmask_b32_e64 v152, v152, -v152, s[74:75]
	v_cvt_pk_bf16_f32 v151, v151, v152
	ds_write2_b64 v121, v[118:119], v[150:151] offset0:4 offset1:6

; #define MFMA32(a, b, c) __builtin_amdgcn_mfma_f32_32x32x16_bf16((a), (b), (c), 0, 0, 0)
; __device__ __forceinline__ void scan_pass1(const ScanP& sp, int b, int h, int seg, LAS unsigned char* lds) {
;     ...
;         if (w < 4) {
; #pragma unroll
;             for (int i = 0; i < 16; ++i) { P1[i] = 0.f; P2[i] = 0.f; }
; #pragma unroll
;             for (int jb = 0; jb < 2; ++jb)
; #pragma unroll
;                 for (int s = 0; s < 2; ++s) {
;                     const bf16x8 hb = pack8(Hacc[jb], s);
;                     const int off = (ln * 72 + 32 * jb + 16 * s + 4 * hh) * 2;
;                     P1 = MFMA32(ld_krow(lds + O_KK + off), hb, P1);
;                     P2 = MFMA32(ld_krow(lds + O_R + off), hb, P2);
;                 }
.LBB0_284:
	s_andn2_b64 vcc, exec, s[0:1]
	s_cbranch_vccnz .LBB0_286
	v_lshlrev_b32_e32 v2, 3, v188
	v_add3_u32 v0, v2, v0, 0
	v_add_u32_e32 v2, 0x8000, v0
	v_add_u32_e32 v0, 0x9000, v0
	ds_read2_b64 v[36:39], v2 offset1:2
	ds_read2_b64 v[68:71], v2 offset0:4 offset1:6
	ds_read2_b64 v[56:59], v0 offset0:64 offset1:66
	ds_read2_b64 v[230:233], v0 offset0:68 offset1:70
	ds_read2_b64 v[234:237], v2 offset0:8 offset1:10
	ds_read2_b64 v[238:241], v0 offset0:72 offset1:74
	ds_read2_b64 v[242:245], v2 offset0:12 offset1:14
	ds_read2_b64 v[246:249], v0 offset0:76 offset1:78
	v_cvt_pk_bf16_f32 v52, v20, v21
	v_cvt_pk_bf16_f32 v53, v22, v23
	v_cvt_pk_bf16_f32 v54, v24, v25
	v_cvt_pk_bf16_f32 v55, v26, v27
	v_cvt_pk_bf16_f32 v72, v28, v29
	v_cvt_pk_bf16_f32 v73, v30, v31
	v_cvt_pk_bf16_f32 v74, v32, v33
	v_cvt_pk_bf16_f32 v75, v34, v35
	s_waitcnt lgkmcnt(7)
	s_nop 0
	v_mfma_f32_32x32x16_bf16 v[36:51], v[36:39], v[52:55], 0
	s_waitcnt lgkmcnt(6)
	v_mfma_f32_32x32x16_bf16 v[36:51], v[68:71], v[72:75], v[36:51]
	s_waitcnt lgkmcnt(5)
	v_mfma_f32_32x32x16_bf16 v[52:67], v[56:59], v[52:55], 0
	s_waitcnt lgkmcnt(4)
	v_mfma_f32_32x32x16_bf16 v[52:67], v[230:233], v[72:75], v[52:67]
	s_nop 1
	v_cvt_pk_bf16_f32 v72, v4, v5
	v_cvt_pk_bf16_f32 v73, v6, v7
	v_cvt_pk_bf16_f32 v74, v8, v9
	v_cvt_pk_bf16_f32 v75, v10, v11
	s_waitcnt lgkmcnt(3)
	s_nop 1
	v_mfma_f32_32x32x16_bf16 v[36:51], v[234:237], v[72:75], v[36:51]
	s_waitcnt lgkmcnt(2)
	v_mfma_f32_32x32x16_bf16 v[52:67], v[238:241], v[72:75], v[52:67]
	s_nop 1
	v_cvt_pk_bf16_f32 v72, v12, v13
	v_cvt_pk_bf16_f32 v73, v14, v15
	v_cvt_pk_bf16_f32 v74, v16, v17
	v_cvt_pk_bf16_f32 v75, v18, v19
	s_waitcnt lgkmcnt(1)
	s_nop 1
	v_mfma_f32_32x32x16_bf16 v[36:51], v[242:245], v[72:75], v[36:51]
	s_waitcnt lgkmcnt(0)
	v_mfma_f32_32x32x16_bf16 v[52:67], v[246:249], v[72:75], v[52:67]
